# v38 with the whole instruction stream shifted by 16 bytes (4 s_nop at entry): code placement trial
# baseline (speedup 1.0000x reference)
; #define LAS __attribute__((address_space(3)))
; __global__ void __launch_bounds__(512, 2) fwd_mega(Args args) {
;     extern __shared__ __attribute__((aligned(16))) unsigned char lds_raw[];
;     LAS unsigned char* lds = (LAS unsigned char*)lds_raw;
;     cg::grid_group grid = cg::this_grid();
;     const int tid = threadIdx.x, lane = tid & 63, wave = __builtin_amdgcn_readfirstlane(tid >> 6);
;     const int G = gridDim.x, bx = blockIdx.x;
;     const float* x = args.in[0]; const float* mem = args.in[1]; const int* positions = (const int*)args.in[2];
;     float* out = args.out;
;     const int lo = args.ph_lo, hi = args.ph_hi;
;     ...
;     if (args.ph_lo < 0) grid.sync();
_Z8fwd_mega4Args:
	s_nop 0
	s_nop 0
	s_nop 0
	s_nop 0
	s_mov_b32 s96, s2
	s_load_dwordx4 s[84:87], s[0:1], 0x100
	s_load_dword s2, s[0:1], 0x110
	s_add_u32 s4, s0, 0x108
	s_addc_u32 s5, s1, 0
	v_and_b32_e32 v196, 0x3ff, v0
	s_waitcnt lgkmcnt(0)
	s_cmp_gt_i32 s84, -1
	v_writelane_b32 v249, s2, 0
	s_movk_i32 s2, 0x3ff
	v_readfirstlane_b32 s10, v196
	s_cbranch_scc1 .LBB0_12
	v_lshrrev_b32_e32 v1, 20, v0
	v_lshrrev_b32_e32 v0, 10, v0
	v_or_b32_e32 v0, v0, v1
	v_and_or_b32 v0, v0, s2, v196
	v_cmp_eq_u32_e32 vcc, 0, v0
	s_barrier
	s_and_saveexec_b64 s[2:3], vcc
	s_cbranch_execz .LBB0_11
	buffer_wbl2 sc1
	s_load_dwordx2 s[4:5], s[4:5], 0x58
	s_mov_b64 s[6:7], exec
	v_mbcnt_lo_u32_b32 v0, s6, 0
	v_mbcnt_hi_u32_b32 v0, s7, v0
	v_cmp_eq_u32_e32 vcc, 0, v0
	s_waitcnt lgkmcnt(0)
	s_load_dword s11, s[4:5], 0x28
	s_and_saveexec_b64 s[8:9], vcc
	s_cbranch_execz .LBB0_4
	s_bcnt1_i32_b64 s6, s[6:7]
	v_mov_b32_e32 v1, 0
	v_mov_b32_e32 v2, s6
	global_atomic_add v1, v1, v2, s[4:5] offset:32 sc0
